# P4 pass 0 reordered: the LoRA prefix item runs first on its wave while the other seven waves take the q/k rows, then all meet in the V-transpose block
# baseline (speedup 1.0000x reference)
.LBB0_772:
	s_or_b64 exec, exec, s[0:1]
	s_add_u32 s0, s28, 0x8f80000
	s_addc_u32 s1, s29, 0
	s_add_u32 s84, s28, 0x9fa0000
	s_addc_u32 s85, s29, 0
	s_cmp_gt_i32 s2, 1
	s_cselect_b64 s[4:5], -1, 0
	v_readlane_b32 s8, v255, 5
	s_mul_i32 s60, s2, 7
	s_add_i32 s60, s60, s8
	s_add_i32 s60, s60, -15
	s_cmpk_lt_i32 s60, 0x4020
	s_cselect_b64 s[6:7], -1, 0
	v_writelane_b32 v255, s0, 38
	v_and_b32_e32 v133, 7, v0
	s_and_b64 s[4:5], s[4:5], s[6:7]
	v_writelane_b32 v255, s1, 39
	s_mov_b32 s0, 0
	v_lshlrev_b32_e32 v132, 3, v133
	s_and_b64 vcc, exec, s[4:5]
	s_waitcnt lgkmcnt(0)
	s_barrier
	s_movk_i32 s9, 0x3e8
	s_cmp_eq_u32 s8, 0
	s_cselect_b32 s9, s2, s9
	s_cmp_lt_u32 s2, 2
	s_cselect_b32 s10, 1, 0
	s_sub_i32 s11, s8, 1
	s_cmp_lt_u32 s11, 2
	s_cselect_b32 s11, s10, 0
	s_lshl_b32 s10, s8, 1
	s_add_i32 s10, s10, s2
	s_addk_i32 s10, 0xfe
	s_cmp_eq_u32 s11, 1
	s_cselect_b32 s9, s10, s9
	v_readlane_b32 s88, v255, 32
	s_cmpk_lt_u32 s9, 0x104
	s_cselect_b32 s10, 1, 0
	v_writelane_b32 v255, s10, 60
	v_writelane_b32 v255, s9, 61
	s_cbranch_scc1 .LBB0_813
	s_cbranch_vccz .LBB0_796
	v_add_u32_e32 v2, s0, v132
	v_readlane_b32 s64, v255, 7
	v_ashrrev_i32_e32 v3, 31, v2
	v_readlane_b32 s65, v255, 8
	s_ashr_i32 s1, s0, 31
	v_mov_b32_e32 v165, 0
	v_lshlrev_b64 v[14:15], 2, v[2:3]
	v_readlane_b32 s66, v255, 9
	v_readlane_b32 s67, v255, 10
	s_mov_b64 s[52:53], s[64:65]
	v_lshl_add_u64 v[10:11], v[164:165], 0, s[0:1]
	v_lshl_add_u64 v[6:7], s[52:53], 0, v[14:15]
	v_lshl_add_u64 v[16:17], v[10:11], 2, s[46:47]
	s_add_i32 s1, s0, 0x200
	v_readlane_b32 s76, v255, 19
	v_readlane_b32 s77, v255, 20
	global_load_dwordx4 v[2:5], v[6:7], off offset:16
	s_nop 0
	global_load_dwordx4 v[6:9], v[6:7], off
	s_nop 0
	global_load_dwordx4 v[10:13], v[16:17], off offset:4
	global_load_dwordx3 v[26:28], v[16:17], off offset:20
	v_add_u32_e32 v16, s1, v164
	v_readlane_b32 s78, v255, 21
	v_readlane_b32 s79, v255, 22
	s_mov_b64 s[54:55], s[66:67]
	s_mov_b64 s[64:65], s[76:77]
	v_add_u32_e32 v30, 3, v16
	s_mov_b64 s[66:67], s[78:79]
	v_ashrrev_i32_e32 v31, 31, v30
	v_lshl_add_u64 v[32:33], v[30:31], 2, s[66:67]
	v_add_u32_e32 v30, 2, v16
	v_add_u32_e32 v18, 7, v16
	v_ashrrev_i32_e32 v31, 31, v30
	v_ashrrev_i32_e32 v19, 31, v18
	v_add_u32_e32 v20, 6, v16
	v_add_u32_e32 v22, 5, v16
	v_add_u32_e32 v24, 4, v16
	v_lshl_add_u64 v[34:35], v[30:31], 2, s[66:67]
	v_add_u32_e32 v30, 1, v16
	v_lshl_add_u64 v[18:19], v[18:19], 2, s[66:67]
	v_ashrrev_i32_e32 v21, 31, v20
	v_ashrrev_i32_e32 v23, 31, v22
	v_ashrrev_i32_e32 v25, 31, v24
	v_ashrrev_i32_e32 v31, 31, v30
	v_lshl_add_u64 v[20:21], v[20:21], 2, s[66:67]
	v_lshl_add_u64 v[22:23], v[22:23], 2, s[66:67]
	v_lshl_add_u64 v[24:25], v[24:25], 2, s[66:67]
	v_lshl_add_u64 v[36:37], v[30:31], 2, s[66:67]
	global_load_dword v29, v[18:19], off
	global_load_dword v31, v[20:21], off
	global_load_dword v39, v[22:23], off
	global_load_dword v56, v[24:25], off
	global_load_dword v57, v[32:33], off
	global_load_dword v58, v[34:35], off
	global_load_dword v59, v[36:37], off
	v_add_u32_e32 v18, s0, v164
	v_ashrrev_i32_e32 v19, 31, v18
	v_lshl_add_u64 v[18:19], v[18:19], 2, s[46:47]
	v_ashrrev_i32_e32 v17, 31, v16
	global_load_dword v60, v[18:19], off
	v_lshl_add_u64 v[16:17], v[16:17], 2, s[66:67]
	v_lshl_add_u64 v[18:19], s[54:55], 0, v[14:15]
	global_load_dword v61, v[16:17], off
	s_nop 0
	global_load_dwordx4 v[14:17], v[18:19], off
	s_nop 0
	global_load_dwordx4 v[18:21], v[18:19], off offset:16
	v_mbcnt_hi_u32_b32 v22, -1, v211
	v_and_b32_e32 v24, 64, v22
	v_xor_b32_e32 v23, 1, v22
	v_add_u32_e32 v24, 64, v24
	v_cmp_lt_i32_e32 vcc, v23, v24
	v_readlane_b32 s6, v255, 32
	v_readlane_b32 s7, v255, 33
	v_cndmask_b32_e32 v23, v22, v23, vcc
	v_lshlrev_b32_e32 v62, 2, v23
	v_xor_b32_e32 v23, 2, v22
	v_cmp_lt_i32_e32 vcc, v23, v24
	s_ashr_i32 s61, s60, 31
	s_movk_i32 s52, 0x6f2
	v_cndmask_b32_e32 v23, v22, v23, vcc
	v_lshlrev_b32_e32 v63, 2, v23
	v_xor_b32_e32 v23, 4, v22
	v_cmp_lt_i32_e32 vcc, v23, v24
	s_lshl_b64 s[6:7], s[60:61], 5
	v_mov_b32_e32 v131, v165
	v_cndmask_b32_e32 v22, v22, v23, vcc
	v_lshlrev_b32_e32 v64, 2, v22
	v_lshlrev_b32_e32 v22, 6, v209
	v_and_or_b32 v30, v22, 64, v132
	v_lshl_or_b32 v22, v209, 2, s6
	v_mov_b32_e32 v23, s7
	s_mov_b64 s[6:7], 0xfd30000
	v_lshl_add_u64 v[32:33], v[22:23], 0, s[6:7]
	v_mov_b32_e32 v22, 0xe40
	v_readlane_b32 s74, v255, 17
	v_readlane_b32 s75, v255, 18
	v_mad_i64_i32 v[34:35], s[6:7], s60, v22, v[130:131]
	v_readlane_b32 s68, v255, 11
	v_readlane_b32 s69, v255, 12
	v_readlane_b32 s70, v255, 13
	s_ashr_i32 s53, s52, 31
	s_mul_hi_i32 s6, s60, 0xc00
	s_mul_i32 s7, s60, 0xc00
	s_mov_b32 s74, 0x6dc9c883
	s_mov_b32 s78, 0xe352b568
	s_mov_b32 s80, 0x1f5fa45
	s_mov_b32 s82, 0xc8c0acee
	s_mov_b32 s86, 0x3fff3717
	s_mov_b32 s88, 0xf20d667d
	s_mov_b32 s90, 0x8e4aa32f
	s_mov_b32 s92, 0xe49b7c16
	v_cmp_gt_u32_e64 s[0:1], 2, v133
	v_cmp_eq_u32_e64 s[4:5], 0, v133
	s_lshl_b64 s[54:55], s[52:53], 5
	s_mul_hi_i32 s63, s52, 0xe40
	s_mul_i32 s62, s52, 0xe40
	v_or_b32_e32 v36, s7, v130
	v_mov_b32_e32 v37, s6
	s_mul_hi_i32 s69, s52, 0xc00
	s_mul_i32 s68, s52, 0xc00
	s_mov_b32 s70, 0x3c800000
	s_mov_b32 s10, 0x800000
	s_mov_b32 s75, 0x3fc45f30
	s_mov_b32 s79, 0x3fc8d275
	s_mov_b32 s81, 0x3fa34119
	s_mov_b32 s83, 0x3f7ddee9
	s_mov_b32 s87, 0x3f572ba4
	s_mov_b32 s89, 0x3f31f91e
	s_mov_b32 s91, 0x3f0be218
	s_mov_b32 s93, 0x3ee5a0f4
	s_mov_b32 s94, 0x3e38aa3b
	s_mov_b32 s11, 0xf800000
	v_mov_b32_e32 v65, 0x260
	v_mov_b32_e32 v38, 0x358637bd
	v_readlane_b32 s71, v255, 14
	v_readlane_b32 s72, v255, 15
	v_readlane_b32 s73, v255, 16
	s_branch .LBB0_775

.LBB0_813:
	v_readlane_b32 s0, v255, 60
	s_nop 0
	s_cmp_eq_u32 s0, 2
	s_cbranch_scc1 .Lp4_redef
	s_add_u32 s4, s28, 0xc980000
	s_addc_u32 s5, s29, 0
	s_add_u32 s16, s28, 0xd9c0000
	v_writelane_b32 v255, s42, 36
	s_addc_u32 s17, s29, 0
	v_lshlrev_b32_e32 v155, 6, v169
	v_writelane_b32 v255, s43, 37
	s_add_u32 s42, s28, 0xea00000
	s_addc_u32 s43, s29, 0
	s_add_u32 s76, s28, 0xfc80000
	s_addc_u32 s77, s29, 0
	v_readlane_b32 s10, v255, 61
	s_add_u32 s68, s28, 0xfc90000
	s_nop 0
	s_addc_u32 s69, s29, 0
	s_nop 0
	s_cmpk_gt_i32 s10, 0x103
	s_cbranch_scc1 .LBB0_900
	v_lshlrev_b32_e32 v66, 5, v166
	v_readlane_b32 s52, v255, 7
	v_or_b32_e32 v6, 0x1800, v66
	v_readlane_b32 s66, v255, 21
	v_readlane_b32 s67, v255, 22
	v_or_b32_e32 v14, 0x1880, v66
	v_or_b32_e32 v22, 0x1900, v66
	v_or_b32_e32 v30, 0x1980, v66
	v_or_b32_e32 v38, 0x1a00, v66
	v_or_b32_e32 v46, 0x1a80, v66
	v_or_b32_e32 v54, 0x1b00, v66
	v_or_b32_e32 v62, 0x1b80, v66
	v_or_b32_e32 v70, 0x1c00, v66
	global_load_dwordx4 v[2:5], v6, s[66:67]
	s_nop 0
	global_load_dwordx4 v[6:9], v6, s[66:67] offset:16
	s_nop 0
	global_load_dwordx4 v[10:13], v14, s[66:67]
	s_nop 0
	global_load_dwordx4 v[14:17], v14, s[66:67] offset:16
	s_nop 0
	global_load_dwordx4 v[18:21], v22, s[66:67] offset:16
	s_waitcnt lgkmcnt(0)
	global_load_dwordx4 v[22:25], v22, s[66:67]
	s_nop 0
	global_load_dwordx4 v[26:29], v30, s[66:67] offset:16
	s_nop 0
	global_load_dwordx4 v[30:33], v30, s[66:67]
	s_nop 0
	global_load_dwordx4 v[34:37], v38, s[66:67]
	s_nop 0
	global_load_dwordx4 v[38:41], v38, s[66:67] offset:16
	s_nop 0
	global_load_dwordx4 v[42:45], v46, s[66:67]
	s_nop 0
	global_load_dwordx4 v[46:49], v46, s[66:67] offset:16
	s_nop 0
	global_load_dwordx4 v[50:53], v54, s[66:67]
	s_nop 0
	global_load_dwordx4 v[54:57], v54, s[66:67] offset:16
	s_nop 0
	global_load_dwordx4 v[58:61], v62, s[66:67]
	s_nop 0
	global_load_dwordx4 v[62:65], v62, s[66:67] offset:16
	s_nop 0
	global_load_dwordx4 v[66:69], v70, s[66:67]
	s_nop 0
	global_load_dwordx4 v[70:73], v70, s[66:67] offset:16
	v_readlane_b32 s0, v255, 27
	v_lshlrev_b32_e32 v110, 4, v166
	v_mov_b32_e32 v111, 0
	v_readlane_b32 s1, v255, 28
	s_lshl_b32 s11, s10, 4
	v_readlane_b32 s56, v255, 11
	v_readlane_b32 s57, v255, 12
	v_readlane_b32 s60, v255, 15
	v_readlane_b32 s61, v255, 16
	v_readlane_b32 s64, v255, 19
	v_readlane_b32 s65, v255, 20
	v_lshl_add_u64 v[116:117], s[0:1], 0, v[110:111]
	s_and_b32 s30, s11, 16
	s_movk_i32 s0, 0xa0
	v_lshl_add_u64 v[112:113], s[76:77], 0, v[110:111]
	v_lshl_add_u64 v[114:115], s[68:69], 0, v[110:111]
	v_lshlrev_b32_e32 v134, 2, v166
	v_lshl_add_u64 v[118:119], s[38:39], 0, v[110:111]
	s_add_i32 s30, s30, 16
	s_lshl_b32 s31, s3, 7
	v_mul_lo_u32 v135, v169, s0
	s_mov_b32 s35, 0x7fc01ff1
	s_movk_i32 s56, 0xe40
	s_mov_b32 s57, 0x3f200000
	s_mov_b32 s60, 0x3fb8aa3b
	s_mov_b32 s61, 0xc2ce8ed0
	s_mov_b32 s64, 0x42b17218
	v_mov_b32_e32 v136, 0x3ca908c9
	s_brev_b32 s65, -2
	s_movk_i32 s66, 0x7fff
	v_mov_b32_e32 v137, 0x7f800000
	v_readlane_b32 s53, v255, 8
	v_readlane_b32 s54, v255, 9
	v_readlane_b32 s55, v255, 10
	v_readlane_b32 s58, v255, 13
	v_readlane_b32 s59, v255, 14
	v_readlane_b32 s62, v255, 17
	v_readlane_b32 s63, v255, 18

.LBB0_900:
	v_readlane_b32 s0, v255, 60
	s_nop 0
	s_cmp_eq_u32 s0, 1
	s_cbranch_scc0 .Lp4_join
	s_mov_b32 s0, 2
	v_writelane_b32 v255, s0, 60
	v_lshlrev_b32_e32 v180, 4, v178
	s_branch .LBB0_796
.Lp4_redef:
	s_add_u32 s4, s28, 0xc980000
	s_addc_u32 s5, s29, 0
	s_add_u32 s16, s28, 0xd9c0000
	s_addc_u32 s17, s29, 0
	v_lshlrev_b32_e32 v155, 6, v169
	s_add_u32 s42, s28, 0xea00000
	s_addc_u32 s43, s29, 0
	s_add_u32 s76, s28, 0xfc80000
	s_addc_u32 s77, s29, 0
	s_add_u32 s68, s28, 0xfc90000
	s_addc_u32 s69, s29, 0
